# MoE down GEMM: row-scale loads issued in the last K iteration with vmcnt re-accounting (epilogue starts without a memory round trip)
# speedup vs baseline: 1.0025x; 1.0025x over previous
.LBB0_1159:
	ds_read_b128 v[144:147], v151
	ds_read_b128 v[154:157], v151 offset:1024
	ds_read_b128 v[158:161], v151 offset:2048
	ds_read_b128 v[162:165], v151 offset:3072
	ds_read_b128 v[166:169], v152
	ds_read_b128 v[170:173], v152 offset:1024
	ds_read_b128 v[174:177], v152 offset:2048
	ds_read_b128 v[178:181], v152 offset:3072
	s_add_u32 s38, s0, 0xfffc0080
	s_addc_u32 s39, s1, -1
	s_cmp_eq_u32 s65, 12
	s_cselect_b32 s41, s25, s39
	s_cselect_b32 s40, s27, s38
	s_cselect_b32 s39, s31, s64
	s_cselect_b32 s38, s30, s29
	v_lshl_add_u64 v[190:191], s[0:1], 0, v[136:137]
	s_add_i32 m0, s37, 0xc000
	ds_read_b128 v[182:185], v153
	ds_read_b128 v[186:189], v153 offset:1024
	ds_read_b128 v[196:199], v153 offset:2048
	ds_read_b128 v[200:203], v153 offset:3072
	ds_read_b128 v[204:207], v153 offset:4096
	ds_read_b128 v[208:211], v153 offset:5120
	ds_read_b128 v[212:215], v153 offset:6144
	ds_read_b128 v[216:219], v153 offset:7168
	global_load_lds_dwordx4 v[190:191], off
	v_lshl_add_u64 v[190:191], s[0:1], 0, v[138:139]
	s_add_i32 m0, s37, 0xe000
	s_nop 0
	global_load_lds_dwordx4 v[190:191], off
	s_waitcnt vmcnt(8)
	s_cmp_lg_u32 s65, 12
	s_cbranch_scc1 .Lrs8_skip
	v_lshl_add_u32 v246, s36, 8, v148
	v_ashrrev_i32_e32 v247, 31, v246
	v_lshl_add_u64 v[244:245], v[246:247], 2, s[12:13]
	global_load_dword v228, v[244:245], off
	global_load_dword v230, v[244:245], off offset:64
	global_load_dword v232, v[244:245], off offset:128
	global_load_dword v234, v[244:245], off offset:192
	global_load_dword v236, v[244:245], off offset:512
	global_load_dword v238, v[244:245], off offset:576
	global_load_dword v240, v[244:245], off offset:640
	global_load_dword v242, v[244:245], off offset:704
.Lrs8_skip:
	s_waitcnt lgkmcnt(0)
	s_barrier
	s_setprio 1
	s_waitcnt lgkmcnt(0)
	v_mfma_f32_16x16x32_bf16 v[124:127], v[144:147], v[182:185], v[124:127]
	v_mfma_f32_16x16x32_bf16 v[120:123], v[158:161], v[182:185], v[120:123]
	v_mfma_f32_16x16x32_bf16 v[108:111], v[144:147], v[196:199], v[108:111]
	v_mfma_f32_16x16x32_bf16 v[104:107], v[158:161], v[196:199], v[104:107]
	v_mfma_f32_16x16x32_bf16 v[92:95], v[144:147], v[204:207], v[92:95]
	v_mfma_f32_16x16x32_bf16 v[88:91], v[158:161], v[204:207], v[88:91]
	v_mfma_f32_16x16x32_bf16 v[84:87], v[144:147], v[212:215], v[84:87]
	v_mfma_f32_16x16x32_bf16 v[76:79], v[158:161], v[212:215], v[76:79]
	v_mfma_f32_16x16x32_bf16 v[124:127], v[154:157], v[186:189], v[124:127]
	v_mfma_f32_16x16x32_bf16 v[120:123], v[162:165], v[186:189], v[120:123]
	v_mfma_f32_16x16x32_bf16 v[108:111], v[154:157], v[200:203], v[108:111]
	v_mfma_f32_16x16x32_bf16 v[104:107], v[162:165], v[200:203], v[104:107]
	v_mfma_f32_16x16x32_bf16 v[92:95], v[154:157], v[208:211], v[92:95]
	v_mfma_f32_16x16x32_bf16 v[88:91], v[162:165], v[208:211], v[88:91]
	v_mfma_f32_16x16x32_bf16 v[84:87], v[154:157], v[216:219], v[84:87]
	v_mfma_f32_16x16x32_bf16 v[76:79], v[162:165], v[216:219], v[76:79]
	s_setprio 0
	s_setprio 1
	v_mfma_f32_16x16x32_bf16 v[116:119], v[166:169], v[182:185], v[116:119]
	v_mfma_f32_16x16x32_bf16 v[112:115], v[174:177], v[182:185], v[112:115]
	v_mfma_f32_16x16x32_bf16 v[100:103], v[166:169], v[196:199], v[100:103]
	v_mfma_f32_16x16x32_bf16 v[96:99], v[174:177], v[196:199], v[96:99]
	v_mfma_f32_16x16x32_bf16 v[80:83], v[166:169], v[204:207], v[80:83]
	v_mfma_f32_16x16x32_bf16 v[72:75], v[174:177], v[204:207], v[72:75]
	v_mfma_f32_16x16x32_bf16 v[68:71], v[166:169], v[212:215], v[68:71]
	v_mfma_f32_16x16x32_bf16 v[64:67], v[174:177], v[212:215], v[64:67]
	v_mfma_f32_16x16x32_bf16 v[116:119], v[170:173], v[186:189], v[116:119]
	v_mfma_f32_16x16x32_bf16 v[112:115], v[178:181], v[186:189], v[112:115]
	v_mfma_f32_16x16x32_bf16 v[100:103], v[170:173], v[200:203], v[100:103]
	v_mfma_f32_16x16x32_bf16 v[96:99], v[178:181], v[200:203], v[96:99]
	v_mfma_f32_16x16x32_bf16 v[80:83], v[170:173], v[208:211], v[80:83]
	v_mfma_f32_16x16x32_bf16 v[72:75], v[178:181], v[208:211], v[72:75]
	v_mfma_f32_16x16x32_bf16 v[68:71], v[170:173], v[216:219], v[68:71]
	v_mfma_f32_16x16x32_bf16 v[64:67], v[178:181], v[216:219], v[64:67]
	s_setprio 0
	s_barrier
	s_add_i32 s66, s55, s46
	v_lshl_add_u64 v[190:191], s[38:39], 0, v[130:131]
	s_mov_b32 m0, s66
	ds_read_b128 v[182:185], v153 offset:16384
	ds_read_b128 v[186:189], v153 offset:17408
	ds_read_b128 v[196:199], v153 offset:18432
	ds_read_b128 v[200:203], v153 offset:19456
	ds_read_b128 v[204:207], v153 offset:20480
	ds_read_b128 v[208:211], v153 offset:21504
	ds_read_b128 v[212:215], v153 offset:22528
	ds_read_b128 v[216:219], v153 offset:23552
	global_load_lds_dwordx4 v[190:191], off
	s_add_i32 m0, s66, 0x2000
	s_add_u32 s66, s38, 0x40000
	v_lshl_add_u64 v[220:221], s[38:39], 0, v[134:135]
	s_addc_u32 s67, s39, 0
	s_add_i32 s68, s58, s46
	global_load_lds_dwordx4 v[220:221], off
	v_lshl_add_u64 v[222:223], s[66:67], 0, v[130:131]
	s_mov_b32 m0, s68
	v_lshl_add_u64 v[224:225], s[40:41], 0, v[132:133]
	global_load_lds_dwordx4 v[222:223], off
	v_lshl_add_u64 v[222:223], s[66:67], 0, v[134:135]
	s_add_i32 m0, s68, 0x2000
	s_nop 0
	global_load_lds_dwordx4 v[222:223], off
	v_lshl_add_u64 v[222:223], s[40:41], 0, v[128:129]
	s_mov_b32 m0, s37
	s_nop 0
	global_load_lds_dwordx4 v[222:223], off
	s_mov_b32 m0, s47
	s_nop 0
	global_load_lds_dwordx4 v[224:225], off
	s_waitcnt vmcnt(16)
	s_cmp_eq_u32 s65, 12
	s_cbranch_scc1 .Lrs8_w2
	s_waitcnt vmcnt(8)
.Lrs8_w2:
	s_waitcnt lgkmcnt(0)
	s_barrier
	s_setprio 1
	s_waitcnt lgkmcnt(0)
	v_mfma_f32_16x16x32_bf16 v[60:63], v[144:147], v[182:185], v[60:63]
	v_mfma_f32_16x16x32_bf16 v[56:59], v[158:161], v[182:185], v[56:59]
	v_mfma_f32_16x16x32_bf16 v[44:47], v[144:147], v[196:199], v[44:47]
	v_mfma_f32_16x16x32_bf16 v[40:43], v[158:161], v[196:199], v[40:43]
	v_mfma_f32_16x16x32_bf16 v[28:31], v[144:147], v[204:207], v[28:31]
	v_mfma_f32_16x16x32_bf16 v[24:27], v[158:161], v[204:207], v[24:27]
	v_mfma_f32_16x16x32_bf16 v[12:15], v[144:147], v[212:215], v[12:15]
	v_mfma_f32_16x16x32_bf16 v[8:11], v[158:161], v[212:215], v[8:11]
	v_mfma_f32_16x16x32_bf16 v[60:63], v[154:157], v[186:189], v[60:63]
	v_mfma_f32_16x16x32_bf16 v[56:59], v[162:165], v[186:189], v[56:59]
	v_mfma_f32_16x16x32_bf16 v[44:47], v[154:157], v[200:203], v[44:47]
	v_mfma_f32_16x16x32_bf16 v[40:43], v[162:165], v[200:203], v[40:43]
	v_mfma_f32_16x16x32_bf16 v[28:31], v[154:157], v[208:211], v[28:31]
	v_mfma_f32_16x16x32_bf16 v[24:27], v[162:165], v[208:211], v[24:27]
	v_mfma_f32_16x16x32_bf16 v[12:15], v[154:157], v[216:219], v[12:15]
	v_mfma_f32_16x16x32_bf16 v[8:11], v[162:165], v[216:219], v[8:11]
	s_setprio 0
	s_setprio 1
	v_mfma_f32_16x16x32_bf16 v[52:55], v[166:169], v[182:185], v[52:55]
	v_mfma_f32_16x16x32_bf16 v[48:51], v[174:177], v[182:185], v[48:51]
	v_mfma_f32_16x16x32_bf16 v[36:39], v[166:169], v[196:199], v[36:39]
	v_mfma_f32_16x16x32_bf16 v[32:35], v[174:177], v[196:199], v[32:35]
	v_mfma_f32_16x16x32_bf16 v[20:23], v[166:169], v[204:207], v[20:23]
	v_mfma_f32_16x16x32_bf16 v[16:19], v[174:177], v[204:207], v[16:19]
	v_mfma_f32_16x16x32_bf16 v[4:7], v[166:169], v[212:215], v[4:7]
	v_mfma_f32_16x16x32_bf16 v[0:3], v[174:177], v[212:215], v[0:3]
	v_mfma_f32_16x16x32_bf16 v[52:55], v[170:173], v[186:189], v[52:55]
	v_mfma_f32_16x16x32_bf16 v[48:51], v[178:181], v[186:189], v[48:51]
	v_mfma_f32_16x16x32_bf16 v[36:39], v[170:173], v[200:203], v[36:39]
	v_mfma_f32_16x16x32_bf16 v[32:35], v[178:181], v[200:203], v[32:35]
	v_mfma_f32_16x16x32_bf16 v[20:23], v[170:173], v[208:211], v[20:23]
	v_mfma_f32_16x16x32_bf16 v[16:19], v[178:181], v[208:211], v[16:19]
	v_mfma_f32_16x16x32_bf16 v[4:7], v[170:173], v[216:219], v[4:7]
	v_mfma_f32_16x16x32_bf16 v[0:3], v[178:181], v[216:219], v[0:3]
	s_setprio 0
	s_barrier
	s_add_i32 s66, 0, 0x18000
	s_add_i32 s67, 0, 0x1c000
	v_add_u32_e32 v162, s66, v149
	v_add_u32_e32 v178, s67, v149
	ds_read_b128 v[144:147], v162
	ds_read_b128 v[154:157], v162 offset:1024
	ds_read_b128 v[158:161], v162 offset:2048
	ds_read_b128 v[162:165], v162 offset:3072
	ds_read_b128 v[166:169], v178
	ds_read_b128 v[170:173], v178 offset:1024
	ds_read_b128 v[174:177], v178 offset:2048
	ds_read_b128 v[178:181], v178 offset:3072
	s_add_u32 s40, s40, 0x40000
	s_addc_u32 s41, s41, 0
	s_mov_b32 m0, s48
	v_lshl_add_u64 v[226:227], s[40:41], 0, v[128:129]
	ds_read_b128 v[182:185], v153 offset:32768
	ds_read_b128 v[186:189], v153 offset:33792
	ds_read_b128 v[196:199], v153 offset:34816
	ds_read_b128 v[200:203], v153 offset:35840
	ds_read_b128 v[204:207], v153 offset:36864
	ds_read_b128 v[208:211], v153 offset:37888
	ds_read_b128 v[212:215], v153 offset:38912
	ds_read_b128 v[216:219], v153 offset:39936
	global_load_lds_dwordx4 v[226:227], off
	v_lshl_add_u64 v[226:227], s[40:41], 0, v[132:133]
	s_mov_b32 m0, s49
	s_nop 0
	global_load_lds_dwordx4 v[226:227], off
	s_waitcnt vmcnt(16)
	s_cmp_eq_u32 s65, 12
	s_cbranch_scc1 .Lrs8_w3
	s_waitcnt vmcnt(8)
.Lrs8_w3:
	s_waitcnt lgkmcnt(0)
	s_barrier
	s_setprio 1
	s_waitcnt lgkmcnt(0)
	v_mfma_f32_16x16x32_bf16 v[124:127], v[144:147], v[182:185], v[124:127]
	v_mfma_f32_16x16x32_bf16 v[120:123], v[158:161], v[182:185], v[120:123]
	v_mfma_f32_16x16x32_bf16 v[108:111], v[144:147], v[196:199], v[108:111]
	v_mfma_f32_16x16x32_bf16 v[104:107], v[158:161], v[196:199], v[104:107]
	v_mfma_f32_16x16x32_bf16 v[92:95], v[144:147], v[204:207], v[92:95]
	v_mfma_f32_16x16x32_bf16 v[88:91], v[158:161], v[204:207], v[88:91]
	v_mfma_f32_16x16x32_bf16 v[84:87], v[144:147], v[212:215], v[84:87]
	v_mfma_f32_16x16x32_bf16 v[76:79], v[158:161], v[212:215], v[76:79]
	v_mfma_f32_16x16x32_bf16 v[124:127], v[154:157], v[186:189], v[124:127]
	v_mfma_f32_16x16x32_bf16 v[120:123], v[162:165], v[186:189], v[120:123]
	v_mfma_f32_16x16x32_bf16 v[108:111], v[154:157], v[200:203], v[108:111]
	v_mfma_f32_16x16x32_bf16 v[104:107], v[162:165], v[200:203], v[104:107]
	v_mfma_f32_16x16x32_bf16 v[92:95], v[154:157], v[208:211], v[92:95]
	v_mfma_f32_16x16x32_bf16 v[88:91], v[162:165], v[208:211], v[88:91]
	v_mfma_f32_16x16x32_bf16 v[84:87], v[154:157], v[216:219], v[84:87]
	v_mfma_f32_16x16x32_bf16 v[76:79], v[162:165], v[216:219], v[76:79]
	s_setprio 0
	s_setprio 1
	v_mfma_f32_16x16x32_bf16 v[116:119], v[166:169], v[182:185], v[116:119]
	v_mfma_f32_16x16x32_bf16 v[112:115], v[174:177], v[182:185], v[112:115]
	v_mfma_f32_16x16x32_bf16 v[100:103], v[166:169], v[196:199], v[100:103]
	v_mfma_f32_16x16x32_bf16 v[96:99], v[174:177], v[196:199], v[96:99]
	v_mfma_f32_16x16x32_bf16 v[80:83], v[166:169], v[204:207], v[80:83]
	v_mfma_f32_16x16x32_bf16 v[72:75], v[174:177], v[204:207], v[72:75]
	v_mfma_f32_16x16x32_bf16 v[68:71], v[166:169], v[212:215], v[68:71]
	v_mfma_f32_16x16x32_bf16 v[64:67], v[174:177], v[212:215], v[64:67]
	v_mfma_f32_16x16x32_bf16 v[116:119], v[170:173], v[186:189], v[116:119]
	v_mfma_f32_16x16x32_bf16 v[112:115], v[178:181], v[186:189], v[112:115]
	v_mfma_f32_16x16x32_bf16 v[100:103], v[170:173], v[200:203], v[100:103]
	v_mfma_f32_16x16x32_bf16 v[96:99], v[178:181], v[200:203], v[96:99]
	v_mfma_f32_16x16x32_bf16 v[80:83], v[170:173], v[208:211], v[80:83]
	v_mfma_f32_16x16x32_bf16 v[72:75], v[178:181], v[208:211], v[72:75]
	v_mfma_f32_16x16x32_bf16 v[68:71], v[170:173], v[216:219], v[68:71]
	v_mfma_f32_16x16x32_bf16 v[64:67], v[178:181], v[216:219], v[64:67]
	s_setprio 0
	s_barrier
	s_add_i32 s40, s66, s46
	v_lshl_add_u64 v[190:191], v[190:191], 0, s[14:15]
	s_mov_b32 m0, s40
	ds_read_b128 v[182:185], v153 offset:49152
	ds_read_b128 v[186:189], v153 offset:50176
	ds_read_b128 v[196:199], v153 offset:51200
	ds_read_b128 v[200:203], v153 offset:52224
	ds_read_b128 v[204:207], v153 offset:53248
	ds_read_b128 v[208:211], v153 offset:54272
	ds_read_b128 v[212:215], v153 offset:55296
	ds_read_b128 v[216:219], v153 offset:56320
	global_load_lds_dwordx4 v[190:191], off
	s_add_i32 m0, s40, 0x2000
	s_add_u32 s38, s38, 0x40080
	v_lshl_add_u64 v[190:191], v[220:221], 0, s[14:15]
	s_addc_u32 s39, s39, 0
	s_add_i32 s40, s67, s46
	global_load_lds_dwordx4 v[190:191], off
	v_lshl_add_u64 v[190:191], s[38:39], 0, v[130:131]
	s_mov_b32 m0, s40
	s_nop 0
	global_load_lds_dwordx4 v[190:191], off
	v_lshl_add_u64 v[190:191], s[38:39], 0, v[134:135]
	s_add_i32 m0, s40, 0x2000
	s_nop 0
	global_load_lds_dwordx4 v[190:191], off
	v_lshl_add_u64 v[190:191], v[222:223], 0, s[14:15]
	s_mov_b32 m0, s51
	s_nop 0
	global_load_lds_dwordx4 v[190:191], off
	v_lshl_add_u64 v[190:191], v[224:225], 0, s[14:15]
	s_mov_b32 m0, s52
	s_nop 0
	global_load_lds_dwordx4 v[190:191], off
	s_waitcnt vmcnt(8)
	s_waitcnt lgkmcnt(0)
	s_barrier
	s_setprio 1
	s_waitcnt lgkmcnt(0)
	v_mfma_f32_16x16x32_bf16 v[60:63], v[144:147], v[182:185], v[60:63]
	v_mfma_f32_16x16x32_bf16 v[56:59], v[158:161], v[182:185], v[56:59]
	v_mfma_f32_16x16x32_bf16 v[44:47], v[144:147], v[196:199], v[44:47]
	v_mfma_f32_16x16x32_bf16 v[40:43], v[158:161], v[196:199], v[40:43]
	v_mfma_f32_16x16x32_bf16 v[28:31], v[144:147], v[204:207], v[28:31]
	v_mfma_f32_16x16x32_bf16 v[24:27], v[158:161], v[204:207], v[24:27]
	v_mfma_f32_16x16x32_bf16 v[12:15], v[144:147], v[212:215], v[12:15]
	v_mfma_f32_16x16x32_bf16 v[8:11], v[158:161], v[212:215], v[8:11]
	v_mfma_f32_16x16x32_bf16 v[60:63], v[154:157], v[186:189], v[60:63]
	v_mfma_f32_16x16x32_bf16 v[56:59], v[162:165], v[186:189], v[56:59]
	v_mfma_f32_16x16x32_bf16 v[44:47], v[154:157], v[200:203], v[44:47]
	v_mfma_f32_16x16x32_bf16 v[40:43], v[162:165], v[200:203], v[40:43]
	v_mfma_f32_16x16x32_bf16 v[28:31], v[154:157], v[208:211], v[28:31]
	v_mfma_f32_16x16x32_bf16 v[24:27], v[162:165], v[208:211], v[24:27]
	v_mfma_f32_16x16x32_bf16 v[12:15], v[154:157], v[216:219], v[12:15]
	v_mfma_f32_16x16x32_bf16 v[8:11], v[162:165], v[216:219], v[8:11]
	s_setprio 0
	s_setprio 1
	v_mfma_f32_16x16x32_bf16 v[52:55], v[166:169], v[182:185], v[52:55]
	v_mfma_f32_16x16x32_bf16 v[48:51], v[174:177], v[182:185], v[48:51]
	v_mfma_f32_16x16x32_bf16 v[36:39], v[166:169], v[196:199], v[36:39]
	v_mfma_f32_16x16x32_bf16 v[32:35], v[174:177], v[196:199], v[32:35]
	v_mfma_f32_16x16x32_bf16 v[20:23], v[166:169], v[204:207], v[20:23]
	v_mfma_f32_16x16x32_bf16 v[16:19], v[174:177], v[204:207], v[16:19]
	v_mfma_f32_16x16x32_bf16 v[4:7], v[166:169], v[212:215], v[4:7]
	v_mfma_f32_16x16x32_bf16 v[0:3], v[174:177], v[212:215], v[0:3]
	v_mfma_f32_16x16x32_bf16 v[52:55], v[170:173], v[186:189], v[52:55]
	v_mfma_f32_16x16x32_bf16 v[48:51], v[178:181], v[186:189], v[48:51]
	v_mfma_f32_16x16x32_bf16 v[36:39], v[170:173], v[200:203], v[36:39]
	v_mfma_f32_16x16x32_bf16 v[32:35], v[178:181], v[200:203], v[32:35]
	v_mfma_f32_16x16x32_bf16 v[20:23], v[170:173], v[208:211], v[20:23]
	v_mfma_f32_16x16x32_bf16 v[16:19], v[178:181], v[208:211], v[16:19]
	v_mfma_f32_16x16x32_bf16 v[4:7], v[170:173], v[216:219], v[4:7]
	v_mfma_f32_16x16x32_bf16 v[0:3], v[178:181], v[216:219], v[0:3]
	s_setprio 0
	s_barrier
	s_add_i32 s65, s65, 2
	s_add_u32 s0, s0, 0x100
	s_addc_u32 s1, s1, 0
	s_add_u32 s29, s29, 0x100
	s_addc_u32 s64, s64, 0
	s_cmp_gt_u32 s65, 13
	s_cbranch_scc0 .LBB0_1159
	s_and_b64 vcc, exec, s[16:17]
	s_cbranch_vccz .LBB0_1162
	s_barrier
.LBB0_1162:
	v_lshl_add_u32 v154, s36, 8, v148
	v_ashrrev_i32_e32 v155, 31, v154
	v_lshl_add_u64 v[144:145], v[154:155], 2, s[12:13]
	v_lshl_or_b32 v146, s63, 8, v150
	v_ashrrev_i32_e32 v147, 31, v146
	v_lshlrev_b64 v[160:161], 11, v[154:155]
	v_or_b32_e32 v158, 16, v154
	v_lshlrev_b64 v[162:163], 1, v[146:147]
	v_lshl_add_u64 v[146:147], s[10:11], 0, v[160:161]
	v_ashrrev_i32_e32 v159, 31, v158
	v_lshl_add_u64 v[146:147], v[146:147], 0, v[162:163]
	v_lshl_add_u64 v[160:161], v[158:159], 2, s[12:13]
	s_nop 0
	v_pk_mul_f32 v[126:127], v[126:127], v[228:229] op_sel_hi:[1,0]
	v_pk_mul_f32 v[124:125], v[124:125], v[228:229] op_sel_hi:[1,0]
	v_pk_mul_f32 v[122:123], v[122:123], v[228:229] op_sel_hi:[1,0]
	v_pk_mul_f32 v[120:121], v[120:121], v[228:229] op_sel_hi:[1,0]
	v_pk_mul_f32 v[118:119], v[118:119], v[228:229] op_sel_hi:[1,0]
	v_pk_mul_f32 v[116:117], v[116:117], v[228:229] op_sel_hi:[1,0]
	v_pk_mul_f32 v[164:165], v[114:115], v[228:229] op_sel_hi:[1,0]
	v_pk_mul_f32 v[156:157], v[112:113], v[228:229] op_sel_hi:[1,0]
	v_cvt_pk_bf16_f32 v112, v124, v125
	v_cvt_pk_bf16_f32 v113, v126, v127
	v_cvt_pk_bf16_f32 v114, v120, v121
	v_cvt_pk_bf16_f32 v115, v122, v123
	global_store_dwordx4 v[146:147], v[112:115], off
	s_nop 1
	v_cvt_pk_bf16_f32 v112, v116, v117
	v_cvt_pk_bf16_f32 v113, v118, v119
	v_cvt_pk_bf16_f32 v114, v156, v157
	v_cvt_pk_bf16_f32 v115, v164, v165
	global_store_dwordx4 v[146:147], v[112:115], off offset:256
	s_nop 0
	v_lshlrev_b64 v[116:117], 11, v[158:159]
	v_or_b32_e32 v114, 32, v154
	v_lshl_add_u64 v[116:117], s[10:11], 0, v[116:117]
	v_ashrrev_i32_e32 v115, 31, v114
	v_lshl_add_u64 v[116:117], v[116:117], 0, v[162:163]
	v_lshl_add_u64 v[118:119], v[114:115], 2, s[12:13]
	s_nop 0
	v_pk_mul_f32 v[110:111], v[110:111], v[230:231] op_sel_hi:[1,0]
	v_pk_mul_f32 v[108:109], v[108:109], v[230:231] op_sel_hi:[1,0]
	v_pk_mul_f32 v[106:107], v[106:107], v[230:231] op_sel_hi:[1,0]
	v_pk_mul_f32 v[104:105], v[104:105], v[230:231] op_sel_hi:[1,0]
	v_pk_mul_f32 v[102:103], v[102:103], v[230:231] op_sel_hi:[1,0]
	v_pk_mul_f32 v[100:101], v[100:101], v[230:231] op_sel_hi:[1,0]
	v_pk_mul_f32 v[120:121], v[98:99], v[230:231] op_sel_hi:[1,0]
	v_pk_mul_f32 v[112:113], v[96:97], v[230:231] op_sel_hi:[1,0]
	v_cvt_pk_bf16_f32 v96, v108, v109
	v_cvt_pk_bf16_f32 v97, v110, v111
	v_cvt_pk_bf16_f32 v98, v104, v105
	v_cvt_pk_bf16_f32 v99, v106, v107
	global_store_dwordx4 v[116:117], v[96:99], off
	s_nop 1
	v_cvt_pk_bf16_f32 v96, v100, v101
	v_cvt_pk_bf16_f32 v97, v102, v103
	v_cvt_pk_bf16_f32 v98, v112, v113
	v_cvt_pk_bf16_f32 v99, v120, v121
	global_store_dwordx4 v[116:117], v[96:99], off offset:256
	s_nop 0
	v_lshlrev_b64 v[100:101], 11, v[114:115]
	v_or_b32_e32 v98, 48, v154
	v_lshl_add_u64 v[100:101], s[10:11], 0, v[100:101]
	v_ashrrev_i32_e32 v99, 31, v98
	v_lshl_add_u64 v[100:101], v[100:101], 0, v[162:163]
	v_lshl_add_u64 v[102:103], v[98:99], 2, s[12:13]
	s_nop 0
	v_pk_mul_f32 v[94:95], v[94:95], v[232:233] op_sel_hi:[1,0]
	v_pk_mul_f32 v[92:93], v[92:93], v[232:233] op_sel_hi:[1,0]
	v_pk_mul_f32 v[90:91], v[90:91], v[232:233] op_sel_hi:[1,0]
	v_pk_mul_f32 v[88:89], v[88:89], v[232:233] op_sel_hi:[1,0]
	v_pk_mul_f32 v[82:83], v[82:83], v[232:233] op_sel_hi:[1,0]
	v_pk_mul_f32 v[80:81], v[80:81], v[232:233] op_sel_hi:[1,0]
	v_pk_mul_f32 v[104:105], v[74:75], v[232:233] op_sel_hi:[1,0]
	v_pk_mul_f32 v[96:97], v[72:73], v[232:233] op_sel_hi:[1,0]
	v_cvt_pk_bf16_f32 v72, v92, v93
	v_cvt_pk_bf16_f32 v73, v94, v95
	v_cvt_pk_bf16_f32 v74, v88, v89
	v_cvt_pk_bf16_f32 v75, v90, v91
	global_store_dwordx4 v[100:101], v[72:75], off
	s_nop 1
	v_cvt_pk_bf16_f32 v72, v80, v81
	v_cvt_pk_bf16_f32 v73, v82, v83
	v_cvt_pk_bf16_f32 v74, v96, v97
	v_cvt_pk_bf16_f32 v75, v104, v105
	global_store_dwordx4 v[100:101], v[72:75], off offset:256
	s_nop 0
	s_nop 0
	v_pk_mul_f32 v[80:81], v[86:87], v[234:235] op_sel_hi:[1,0]
	v_lshlrev_b64 v[74:75], 11, v[98:99]
	v_lshl_add_u64 v[74:75], s[10:11], 0, v[74:75]
	v_lshl_add_u64 v[74:75], v[74:75], 0, v[162:163]
	v_pk_mul_f32 v[82:83], v[84:85], v[234:235] op_sel_hi:[1,0]
	v_pk_mul_f32 v[78:79], v[78:79], v[234:235] op_sel_hi:[1,0]
	v_pk_mul_f32 v[76:77], v[76:77], v[234:235] op_sel_hi:[1,0]
	v_pk_mul_f32 v[70:71], v[70:71], v[234:235] op_sel_hi:[1,0]
	v_pk_mul_f32 v[68:69], v[68:69], v[234:235] op_sel_hi:[1,0]
	v_pk_mul_f32 v[84:85], v[66:67], v[234:235] op_sel_hi:[1,0]
	v_pk_mul_f32 v[72:73], v[64:65], v[234:235] op_sel_hi:[1,0]
	v_cvt_pk_bf16_f32 v64, v82, v83
	v_cvt_pk_bf16_f32 v65, v80, v81
	v_cvt_pk_bf16_f32 v66, v76, v77
	v_cvt_pk_bf16_f32 v67, v78, v79
	global_store_dwordx4 v[74:75], v[64:67], off
	s_nop 1
	v_cvt_pk_bf16_f32 v64, v68, v69
	v_cvt_pk_bf16_f32 v65, v70, v71
	v_cvt_pk_bf16_f32 v66, v72, v73
	v_cvt_pk_bf16_f32 v67, v84, v85
	global_store_dwordx4 v[74:75], v[64:67], off offset:256
	s_nop 0
	v_add_co_u32_e32 v68, vcc, s59, v146
	v_lshl_add_u64 v[66:67], v[146:147], 0, s[6:7]
	s_nop 0
	v_addc_co_u32_e32 v69, vcc, 0, v147, vcc
	s_nop 0
	v_pk_mul_f32 v[62:63], v[62:63], v[236:237] op_sel_hi:[1,0]
	v_pk_mul_f32 v[60:61], v[60:61], v[236:237] op_sel_hi:[1,0]
	v_pk_mul_f32 v[58:59], v[58:59], v[236:237] op_sel_hi:[1,0]
	v_pk_mul_f32 v[56:57], v[56:57], v[236:237] op_sel_hi:[1,0]
	v_pk_mul_f32 v[54:55], v[54:55], v[236:237] op_sel_hi:[1,0]
	v_pk_mul_f32 v[52:53], v[52:53], v[236:237] op_sel_hi:[1,0]
	v_pk_mul_f32 v[70:71], v[50:51], v[236:237] op_sel_hi:[1,0]
	v_pk_mul_f32 v[64:65], v[48:49], v[236:237] op_sel_hi:[1,0]
	v_cvt_pk_bf16_f32 v48, v60, v61
	v_cvt_pk_bf16_f32 v49, v62, v63
	v_cvt_pk_bf16_f32 v50, v56, v57
	v_cvt_pk_bf16_f32 v51, v58, v59
	global_store_dwordx4 v[68:69], v[48:51], off
	s_nop 1
	v_cvt_pk_bf16_f32 v48, v52, v53
	v_cvt_pk_bf16_f32 v49, v54, v55
	v_cvt_pk_bf16_f32 v50, v64, v65
	v_cvt_pk_bf16_f32 v51, v70, v71
	global_store_dwordx4 v[66:67], v[48:51], off offset:256
	s_nop 0
	v_add_co_u32_e32 v52, vcc, s60, v146
	v_lshl_add_u64 v[50:51], v[146:147], 0, s[18:19]
	s_nop 0
	v_addc_co_u32_e32 v53, vcc, 0, v147, vcc
	s_nop 0
	v_pk_mul_f32 v[46:47], v[46:47], v[238:239] op_sel_hi:[1,0]
	v_pk_mul_f32 v[44:45], v[44:45], v[238:239] op_sel_hi:[1,0]
	v_pk_mul_f32 v[42:43], v[42:43], v[238:239] op_sel_hi:[1,0]
	v_pk_mul_f32 v[40:41], v[40:41], v[238:239] op_sel_hi:[1,0]
	v_pk_mul_f32 v[38:39], v[38:39], v[238:239] op_sel_hi:[1,0]
	v_pk_mul_f32 v[36:37], v[36:37], v[238:239] op_sel_hi:[1,0]
	v_pk_mul_f32 v[54:55], v[34:35], v[238:239] op_sel_hi:[1,0]
	v_pk_mul_f32 v[48:49], v[32:33], v[238:239] op_sel_hi:[1,0]
	v_cvt_pk_bf16_f32 v32, v44, v45
	v_cvt_pk_bf16_f32 v33, v46, v47
	v_cvt_pk_bf16_f32 v34, v40, v41
	v_cvt_pk_bf16_f32 v35, v42, v43
	global_store_dwordx4 v[52:53], v[32:35], off
	s_nop 1
	v_cvt_pk_bf16_f32 v32, v36, v37
	v_cvt_pk_bf16_f32 v33, v38, v39
	v_cvt_pk_bf16_f32 v34, v48, v49
	v_cvt_pk_bf16_f32 v35, v54, v55
	global_store_dwordx4 v[50:51], v[32:35], off offset:256
	s_nop 0
	v_add_co_u32_e32 v36, vcc, s61, v146
	v_lshl_add_u64 v[34:35], v[146:147], 0, s[20:21]
	s_nop 0
	v_addc_co_u32_e32 v37, vcc, 0, v147, vcc
	s_and_b64 vcc, exec, s[2:3]
	s_nop 0
	v_pk_mul_f32 v[30:31], v[30:31], v[240:241] op_sel_hi:[1,0]
	v_pk_mul_f32 v[28:29], v[28:29], v[240:241] op_sel_hi:[1,0]
	v_pk_mul_f32 v[26:27], v[26:27], v[240:241] op_sel_hi:[1,0]
	v_pk_mul_f32 v[24:25], v[24:25], v[240:241] op_sel_hi:[1,0]
	v_pk_mul_f32 v[22:23], v[22:23], v[240:241] op_sel_hi:[1,0]
	v_pk_mul_f32 v[20:21], v[20:21], v[240:241] op_sel_hi:[1,0]
	v_pk_mul_f32 v[38:39], v[18:19], v[240:241] op_sel_hi:[1,0]
	v_pk_mul_f32 v[32:33], v[16:17], v[240:241] op_sel_hi:[1,0]
	v_cvt_pk_bf16_f32 v16, v28, v29
	v_cvt_pk_bf16_f32 v17, v30, v31
	v_cvt_pk_bf16_f32 v18, v24, v25
	v_cvt_pk_bf16_f32 v19, v26, v27
	global_store_dwordx4 v[36:37], v[16:19], off
	s_nop 1
	v_cvt_pk_bf16_f32 v16, v20, v21
	v_cvt_pk_bf16_f32 v17, v22, v23
	v_cvt_pk_bf16_f32 v18, v32, v33
	v_cvt_pk_bf16_f32 v19, v38, v39
	global_store_dwordx4 v[34:35], v[16:19], off offset:256
	s_nop 0
	v_add_co_u32_e64 v20, s[0:1], s62, v146
	v_lshl_add_u64 v[18:19], v[146:147], 0, s[22:23]
	s_nop 0
	v_addc_co_u32_e64 v21, s[0:1], 0, v147, s[0:1]
	s_mov_b64 s[0:1], -1
	s_nop 0
	v_pk_mul_f32 v[14:15], v[14:15], v[242:243] op_sel_hi:[1,0]
	v_pk_mul_f32 v[12:13], v[12:13], v[242:243] op_sel_hi:[1,0]
	v_pk_mul_f32 v[10:11], v[10:11], v[242:243] op_sel_hi:[1,0]
	v_pk_mul_f32 v[8:9], v[8:9], v[242:243] op_sel_hi:[1,0]
	v_pk_mul_f32 v[6:7], v[6:7], v[242:243] op_sel_hi:[1,0]
	v_pk_mul_f32 v[4:5], v[4:5], v[242:243] op_sel_hi:[1,0]
	v_pk_mul_f32 v[22:23], v[2:3], v[242:243] op_sel_hi:[1,0]
	v_pk_mul_f32 v[16:17], v[0:1], v[242:243] op_sel_hi:[1,0]
	v_cvt_pk_bf16_f32 v0, v12, v13
	v_cvt_pk_bf16_f32 v1, v14, v15
	v_cvt_pk_bf16_f32 v2, v8, v9
	v_cvt_pk_bf16_f32 v3, v10, v11
	global_store_dwordx4 v[20:21], v[0:3], off
	s_nop 1
	v_cvt_pk_bf16_f32 v0, v4, v5
	v_cvt_pk_bf16_f32 v1, v6, v7
	v_cvt_pk_bf16_f32 v2, v16, v17
	v_cvt_pk_bf16_f32 v3, v22, v23
	global_store_dwordx4 v[18:19], v[0:3], off offset:256
	s_cbranch_vccnz .LBB0_1149
	s_andn2_b64 vcc, exec, s[8:9]
	s_cbranch_vccnz .LBB0_1148
	s_barrier
	s_branch .LBB0_1148
